# loop-edge edits (docs 7.11/7.12) in both attention loops: known-false v_cmp+branch removed with rare rescale block moved out of line; loop-carried bookkeeping hoisted in front of the loop-back barrier
# speedup vs baseline: 1.0050x; 1.0038x over previous
; #define SBAR() __builtin_amdgcn_sched_barrier(0)
; __device__ __forceinline__ float qkt_deep(f32x16& p0, f32x16& p1, const int (&ka)[4], const bf16x8 (&qr)[8]) {
;     ...
;   QD_RD0(0); QD_RD0(1); QD_RD0(2); QD_RD0(3); QD_RD0(4); QD_RD0(5); QD_RD0(6); QD_RD0(7);
;   QK_WAIT(7); QD_MM0(0); SBAR(); QD_RD1(0);
;   QK_WAIT(7); QD_MM0(1); SBAR(); QD_RD1(1);
;   QK_WAIT(7); QD_MM0(2); SBAR(); QD_RD1(2);
;   QK_WAIT(7); QD_MM0(3); SBAR(); QD_RD1(3);
;   QK_WAIT(7); QD_MM0(4); SBAR(); QD_RD1(4);
;   QK_WAIT(7); QD_MM0(5); SBAR(); QD_RD1(5);
;   QK_WAIT(7); QD_MM0(6); SBAR(); QD_RD1(6);
;   QK_WAIT(7); QD_MM0(7); SBAR(); QD_RD1(7);
;   QK_WAIT(7); QD_MM1(0); pm = fmaxf(p0[0], p0[1]); SBAR();
;   QK_WAIT(6); QD_MM1(1); pm = fmaxf(fmaxf(pm, p0[2]), p0[3]); SBAR();
;   QK_WAIT(5); QD_MM1(2); pm = fmaxf(fmaxf(pm, p0[4]), p0[5]); SBAR();
;   QK_WAIT(4); QD_MM1(3); pm = fmaxf(fmaxf(pm, p0[6]), p0[7]); SBAR();
;   QK_WAIT(3); QD_MM1(4); pm = fmaxf(fmaxf(pm, p0[8]), p0[9]); SBAR();
;   QK_WAIT(2); QD_MM1(5); pm = fmaxf(fmaxf(pm, p0[10]), p0[11]); SBAR();
;   QK_WAIT(1); QD_MM1(6); pm = fmaxf(fmaxf(pm, p0[12]), p0[13]); SBAR();
;   QK_WAIT(0); QD_MM1(7); pm = fmaxf(fmaxf(pm, p0[14]), p0[15]);
;   return pm;
; }
; template <int LD>
; __device__ __forceinline__ void attn256_body(const bf16_t* __restrict__ Qb, const bf16_t* __restrict__ Kh, const unsigned char* __restrict__ Vimg, int seq, char* lds, LAS unsigned char* ldsl,
;                                              f32x16 (&o)[8], float (&rli)[16]) {
;     ...
;   for (int j = 0; j < NT; ++j) {
;     const int cur = j & 1;
;     if (j + 1 < NT) { if (cur) A2_DMA(0, (j + 1) * 64); else A2_DMA(1, (j + 1) * 64); }
;     f32x16 p0 = f32x16{}, p1 = f32x16{}; float pmax;
;     { int ka[4];
; #pragma unroll
;       for (int q = 0; q < 4; ++q) ka[q] = kbase + cur * A2_STAGE + (((2 * q + hi) ^ (r32 & 7)) << 4);
;       pmax = qkt_deep(p0, p1, ka, qr); }
; #pragma unroll
;     for (int r = 0; r < 16; ++r) pmax = fmaxf(pmax, p1[r]);
;     pmax = half_swap_max(pmax);
;     float mn, alpha;
;     if (__builtin_expect(__all(pmax - m_reg <= ATT_THR / ATT_SCALE), 1)) { mn = m_reg; alpha = 1.f; }
;     else { mn = fmaxf(m_reg, pmax); alpha = __builtin_amdgcn_exp2f((m_reg - mn) * C); m_reg = mn; }
;     const float mnC = -mn * C; float ps;
;     if (__any(alpha < 1.f)) { if (hi == 0) al_l[r32] = alpha; asm volatile("s_waitcnt lgkmcnt(0)" ::: "memory");
.LBB0_663:
	s_mul_i32 s4, s4, 0xc000
	s_waitcnt lgkmcnt(0)
	v_add_u32_e32 v0, s4, v221
	v_add_u32_e32 v14, v0, v233
	v_add_u32_e32 v15, v0, v234
	v_add_u32_e32 v252, v0, v235
	v_add_u32_e32 v0, v0, v236
	ds_read_b128 v[2:5], v14 offset:0
	ds_read_b128 v[6:9], v15 offset:0
	ds_read_b128 v[10:13], v252 offset:0
	ds_read_b128 v[144:147], v0 offset:0
	ds_read_b128 v[148:151], v14 offset:0x80
	ds_read_b128 v[152:155], v15 offset:0x80
	ds_read_b128 v[156:159], v252 offset:0x80
	ds_read_b128 v[208:211], v0 offset:0x80
	s_waitcnt lgkmcnt(7)
	s_nop 0
	v_mfma_f32_32x32x16_bf16 v[160:175], v[2:5], v[176:179], 0
	ds_read_b128 v[2:5], v14 offset:0x2000
	s_waitcnt lgkmcnt(7)
	s_nop 0
	v_mfma_f32_32x32x16_bf16 v[160:175], v[6:9], v[180:183], v[160:175]
	ds_read_b128 v[6:9], v15 offset:0x2000
	s_waitcnt lgkmcnt(7)
	s_nop 0
	v_mfma_f32_32x32x16_bf16 v[160:175], v[10:13], v[184:187], v[160:175]
	ds_read_b128 v[10:13], v252 offset:0x2000
	s_waitcnt lgkmcnt(7)
	s_nop 0
	v_mfma_f32_32x32x16_bf16 v[160:175], v[144:147], v[188:191], v[160:175]
	ds_read_b128 v[240:243], v0 offset:0x2000
	s_waitcnt lgkmcnt(7)
	s_nop 0
	v_mfma_f32_32x32x16_bf16 v[160:175], v[148:151], v[192:195], v[160:175]
	ds_read_b128 v[244:247], v14 offset:0x2080
	s_waitcnt lgkmcnt(7)
	s_nop 0
	v_mfma_f32_32x32x16_bf16 v[160:175], v[152:155], v[196:199], v[160:175]
	ds_read_b128 v[248:251], v15 offset:0x2080
	s_waitcnt lgkmcnt(7)
	s_nop 0
	v_mfma_f32_32x32x16_bf16 v[160:175], v[156:159], v[200:203], v[160:175]
	ds_read_b128 v[212:215], v252 offset:0x2080
	s_waitcnt lgkmcnt(7)
	s_nop 0
	v_mfma_f32_32x32x16_bf16 v[160:175], v[208:211], v[204:207], v[160:175]
	ds_read_b128 v[208:211], v0 offset:0x2080
	s_waitcnt lgkmcnt(7)
	v_mfma_f32_32x32x16_bf16 v[144:159], v[2:5], v[176:179], 0
	s_nop 10
	v_max_f32_e32 v0, v161, v161
	v_max_f32_e32 v2, v160, v160
	v_max_f32_e32 v0, v2, v0
	s_waitcnt lgkmcnt(6)
	s_nop 0
	v_mfma_f32_32x32x16_bf16 v[144:159], v[6:9], v[180:183], v[144:159]
	v_max3_f32 v0, v0, v162, v163
	s_waitcnt lgkmcnt(5)
	s_nop 0
	v_mfma_f32_32x32x16_bf16 v[144:159], v[10:13], v[184:187], v[144:159]
	v_max3_f32 v0, v0, v164, v165
	s_waitcnt lgkmcnt(4)
	s_nop 0
	v_mfma_f32_32x32x16_bf16 v[144:159], v[240:243], v[188:191], v[144:159]
	v_max3_f32 v0, v0, v166, v167
	s_waitcnt lgkmcnt(3)
	s_nop 0
	v_mfma_f32_32x32x16_bf16 v[144:159], v[244:247], v[192:195], v[144:159]
	v_max3_f32 v0, v0, v168, v169
	s_waitcnt lgkmcnt(2)
	s_nop 0
	v_mfma_f32_32x32x16_bf16 v[144:159], v[248:251], v[196:199], v[144:159]
	v_max3_f32 v0, v0, v170, v171
	s_waitcnt lgkmcnt(1)
	s_nop 0
	v_mfma_f32_32x32x16_bf16 v[144:159], v[212:215], v[200:203], v[144:159]
	v_max3_f32 v0, v0, v172, v173
	s_waitcnt lgkmcnt(0)
	s_nop 0
	v_mfma_f32_32x32x16_bf16 v[144:159], v[208:211], v[204:207], v[144:159]
	v_max3_f32 v0, v0, v174, v175
	s_nop 10
	v_max3_f32 v0, v0, v144, v145
	v_max3_f32 v0, v0, v146, v147
	v_max3_f32 v0, v0, v148, v149
	v_max3_f32 v0, v0, v150, v151
	v_max3_f32 v0, v0, v152, v153
	v_max3_f32 v0, v0, v154, v155
	v_max3_f32 v0, v0, v156, v157
	v_max3_f32 v0, v0, v158, v159
	v_mov_b32_e32 v2, v0
	s_nop 1
	v_permlane32_swap_b32_e32 v0, v2
	v_max_f32_e32 v2, v2, v2
	v_max_f32_e32 v0, v0, v0
	v_max_f32_e32 v2, v0, v2
	v_sub_f32_e32 v0, v2, v238
	v_cmp_ge_f32_e32 vcc, s93, v0
	s_cmp_eq_u64 vcc, exec
	v_mov_b32_e32 v0, 1.0
	s_cbranch_scc0 .LBB0_670
.LBB0_668:
	v_mul_f32_e32 v14, 0xbe0293ee, v238
	v_fmamk_f32 v2, v160, 0x3e0293ee, v14
	v_exp_f32_e32 v2, v2
	v_fmamk_f32 v3, v161, 0x3e0293ee, v14
	v_exp_f32_e32 v3, v3
	v_fmamk_f32 v4, v162, 0x3e0293ee, v14
	v_exp_f32_e32 v4, v4
	v_fmamk_f32 v5, v163, 0x3e0293ee, v14
	v_exp_f32_e32 v5, v5
	v_fmamk_f32 v7, v164, 0x3e0293ee, v14
	v_add_f32_e32 v6, 0, v2
	v_exp_f32_e32 v7, v7
	v_fmamk_f32 v8, v165, 0x3e0293ee, v14
	v_add_f32_e32 v6, v3, v6
	v_exp_f32_e32 v8, v8
	v_fmamk_f32 v9, v166, 0x3e0293ee, v14
	v_add_f32_e32 v6, v4, v6
	v_exp_f32_e32 v9, v9
	v_fmamk_f32 v10, v167, 0x3e0293ee, v14
	v_add_f32_e32 v6, v5, v6
	v_exp_f32_e32 v10, v10
	v_add_f32_e32 v6, v7, v6
	v_cvt_pk_bf16_f32 v2, v2, v3
	v_cvt_pk_bf16_f32 v3, v4, v5
	v_cvt_pk_bf16_f32 v4, v7, v8
	v_cvt_pk_bf16_f32 v5, v9, v10
	s_waitcnt lgkmcnt(0)
	v_add_f32_e32 v6, v8, v6
	s_add_i32 s45, s45, 1
	v_add_f32_e32 v6, v9, v6
	v_permlane32_swap_b32_e32 v2, v4
	v_add_u32_e32 v15, s4, v237
	v_add_f32_e32 v248, v10, v6
	v_permlane32_swap_b32_e32 v3, v5
	ds_read_b64_tr_b16 v[6:7], v15 offset:0
	ds_read_b64_tr_b16 v[8:9], v15 offset:0x800
	ds_read_b64_tr_b16 v[10:11], v15 offset:0x200
	ds_read_b64_tr_b16 v[12:13], v15 offset:0xa00
	ds_read_b64_tr_b16 v[160:161], v15 offset:0x400
	ds_read_b64_tr_b16 v[162:163], v15 offset:0xc00
	ds_read_b64_tr_b16 v[164:165], v15 offset:0x600
	ds_read_b64_tr_b16 v[166:167], v15 offset:0xe00
	v_add_u32_e32 v249, 0x4000, v15
	ds_read_b64_tr_b16 v[208:209], v249 offset:0
	ds_read_b64_tr_b16 v[210:211], v249 offset:0x800
	ds_read_b64_tr_b16 v[212:213], v249 offset:0x200
	ds_read_b64_tr_b16 v[214:215], v249 offset:0xa00
	ds_read_b64_tr_b16 v[240:241], v249 offset:0x400
	ds_read_b64_tr_b16 v[242:243], v249 offset:0xc00
	ds_read_b64_tr_b16 v[244:245], v249 offset:0x600
	ds_read_b64_tr_b16 v[246:247], v249 offset:0xe00
	s_waitcnt lgkmcnt(8)
; #define SBAR() __builtin_amdgcn_sched_barrier(0)
; #define LGKM_WAIT8() do { asm volatile("s_waitcnt lgkmcnt(8)" ::: "memory"); SBAR(); } while (0)
; #define LGKM_WAIT0() do { asm volatile("s_waitcnt lgkmcnt(0)" ::: "memory"); SBAR(); } while (0)
; #define EX4(P, B) do { _Pragma("unroll") for (int r_ = (B); r_ < (B) + 4; ++r_) { P[r_] = __builtin_amdgcn_exp2f(fmaf(P[r_], C, mnC)); ps += P[r_]; } } while (0)
; __device__ __forceinline__ void exp_pv256(f32x16 (&o)[8], f32x16& p0, f32x16& p1, int vb, float C, float mnC, float& ps) {
;   VG4 fa, fb; bf16x8 pa, pn;
;   ps = 0.f;
;   EX4(p0, 0); EX4(p0, 4); pa = pk4<0>(p0);
;   asm volatile("s_waitcnt lgkmcnt(0)" ::: "memory"); SBAR();
;   vg4_read<0>(fa, vb); vg4_read<0>(fb, vb + 16384);
;   LGKM_WAIT8(); vg4_mma<0>(o, fa, pa); EX4(p0, 8); SBAR();
;   vg4_read<1>(fa, vb); LGKM_WAIT8(); vg4_mma<1>(o, fb, pa); EX4(p0, 12); pn = pk4<8>(p0); SBAR();
;   vg4_read<1>(fb, vb + 16384); LGKM_WAIT8(); vg4_mma<0>(o, fa, pn); EX4(p1, 0); SBAR();
;   vg4_read<2>(fa, vb); LGKM_WAIT8(); vg4_mma<1>(o, fb, pn); EX4(p1, 4); pa = pk4<0>(p1); SBAR();
;   vg4_read<2>(fb, vb + 16384); LGKM_WAIT8(); vg4_mma<0>(o, fa, pa); EX4(p1, 8); SBAR();
;   vg4_read<3>(fa, vb); LGKM_WAIT8(); vg4_mma<1>(o, fb, pa); EX4(p1, 12); pn = pk4<8>(p1); SBAR();
;   vg4_read<3>(fb, vb + 16384); LGKM_WAIT8(); vg4_mma<0>(o, fa, pn); SBAR();
;   LGKM_WAIT0(); vg4_mma<1>(o, fb, pn);
	s_nop 0
	v_mfma_f32_32x32x16_bf16 v[128:143], v[2:5], v[6:9], v[128:143]
	v_fmamk_f32 v6, v168, 0x3e0293ee, v14
	v_exp_f32_e32 v168, v6
	v_fmamk_f32 v6, v169, 0x3e0293ee, v14
	v_exp_f32_e32 v169, v6
	v_fmamk_f32 v6, v170, 0x3e0293ee, v14
	v_exp_f32_e32 v170, v6
	v_fmamk_f32 v6, v171, 0x3e0293ee, v14
	v_mfma_f32_32x32x16_bf16 v[112:127], v[2:5], v[10:13], v[112:127]
	v_exp_f32_e32 v171, v6
	v_add_f32_e32 v6, v168, v248
	v_add_f32_e32 v6, v169, v6
	v_add_f32_e32 v6, v170, v6
	v_add_f32_e32 v248, v171, v6
	v_mfma_f32_32x32x16_bf16 v[96:111], v[2:5], v[160:163], v[96:111]
	v_mfma_f32_32x32x16_bf16 v[80:95], v[2:5], v[164:167], v[80:95]
	ds_read_b64_tr_b16 v[6:7], v15 offset:0x1000
	ds_read_b64_tr_b16 v[8:9], v15 offset:0x1800
	ds_read_b64_tr_b16 v[10:11], v15 offset:0x1200
	ds_read_b64_tr_b16 v[12:13], v15 offset:0x1a00
	ds_read_b64_tr_b16 v[160:161], v15 offset:0x1400
	ds_read_b64_tr_b16 v[162:163], v15 offset:0x1c00
	ds_read_b64_tr_b16 v[164:165], v15 offset:0x1600
	ds_read_b64_tr_b16 v[166:167], v15 offset:0x1e00
	s_waitcnt lgkmcnt(8)
	v_mfma_f32_32x32x16_bf16 v[64:79], v[2:5], v[208:211], v[64:79]
	v_fmamk_f32 v172, v172, 0x3e0293ee, v14
	v_exp_f32_e32 v172, v172
	v_fmamk_f32 v173, v173, 0x3e0293ee, v14
	v_exp_f32_e32 v173, v173
	v_fmamk_f32 v174, v174, 0x3e0293ee, v14
	v_exp_f32_e32 v174, v174
	v_fmamk_f32 v175, v175, 0x3e0293ee, v14
	v_mfma_f32_32x32x16_bf16 v[48:63], v[2:5], v[212:215], v[48:63]
	v_exp_f32_e32 v175, v175
	v_add_f32_e32 v208, v172, v248
	v_add_f32_e32 v208, v173, v208
	v_add_f32_e32 v208, v174, v208
	v_cvt_pk_bf16_f32 v168, v168, v169
	v_cvt_pk_bf16_f32 v169, v170, v171
	v_cvt_pk_bf16_f32 v170, v172, v173
	v_mfma_f32_32x32x16_bf16 v[32:47], v[2:5], v[240:243], v[32:47]
	v_cvt_pk_bf16_f32 v171, v174, v175
	v_add_f32_e32 v248, v175, v208
	v_permlane32_swap_b32_e32 v168, v170
	v_permlane32_swap_b32_e32 v169, v171
	v_mfma_f32_32x32x16_bf16 v[16:31], v[2:5], v[244:247], v[16:31]
	ds_read_b64_tr_b16 v[2:3], v249 offset:0x1000
	ds_read_b64_tr_b16 v[4:5], v249 offset:0x1800
	ds_read_b64_tr_b16 v[172:173], v249 offset:0x1200
	ds_read_b64_tr_b16 v[174:175], v249 offset:0x1a00
	ds_read_b64_tr_b16 v[208:209], v249 offset:0x1400
	ds_read_b64_tr_b16 v[210:211], v249 offset:0x1c00
	ds_read_b64_tr_b16 v[212:213], v249 offset:0x1600
	ds_read_b64_tr_b16 v[214:215], v249 offset:0x1e00
	s_waitcnt lgkmcnt(8)
	s_nop 0
	v_mfma_f32_32x32x16_bf16 v[128:143], v[168:171], v[6:9], v[128:143]
	v_fmamk_f32 v6, v144, 0x3e0293ee, v14
	v_exp_f32_e32 v240, v6
	v_fmamk_f32 v6, v145, 0x3e0293ee, v14
	v_exp_f32_e32 v241, v6
	v_fmamk_f32 v6, v146, 0x3e0293ee, v14
	v_exp_f32_e32 v242, v6
	v_fmamk_f32 v6, v147, 0x3e0293ee, v14
	v_mfma_f32_32x32x16_bf16 v[112:127], v[168:171], v[10:13], v[112:127]
	v_exp_f32_e32 v243, v6
	v_add_f32_e32 v6, v240, v248
	v_add_f32_e32 v6, v241, v6
	v_add_f32_e32 v6, v242, v6
	v_add_f32_e32 v244, v243, v6
	v_mfma_f32_32x32x16_bf16 v[96:111], v[168:171], v[160:163], v[96:111]
	v_mfma_f32_32x32x16_bf16 v[80:95], v[168:171], v[164:167], v[80:95]
	ds_read_b64_tr_b16 v[6:7], v15 offset:0x2000
	ds_read_b64_tr_b16 v[8:9], v15 offset:0x2800
	ds_read_b64_tr_b16 v[10:11], v15 offset:0x2200
	ds_read_b64_tr_b16 v[12:13], v15 offset:0x2a00
	ds_read_b64_tr_b16 v[144:145], v15 offset:0x2400
	ds_read_b64_tr_b16 v[146:147], v15 offset:0x2c00
	ds_read_b64_tr_b16 v[160:161], v15 offset:0x2600
	ds_read_b64_tr_b16 v[162:163], v15 offset:0x2e00
	s_waitcnt lgkmcnt(8)
	v_mfma_f32_32x32x16_bf16 v[64:79], v[168:171], v[2:5], v[64:79]
	v_fmamk_f32 v2, v148, 0x3e0293ee, v14
	v_exp_f32_e32 v4, v2
	v_fmamk_f32 v2, v149, 0x3e0293ee, v14
	v_exp_f32_e32 v5, v2
	v_fmamk_f32 v2, v150, 0x3e0293ee, v14
	v_exp_f32_e32 v148, v2
	v_fmamk_f32 v2, v151, 0x3e0293ee, v14
	v_mfma_f32_32x32x16_bf16 v[48:63], v[168:171], v[172:175], v[48:63]
	v_exp_f32_e32 v149, v2
	v_add_f32_e32 v2, v4, v244
	v_add_f32_e32 v2, v5, v2
	v_add_f32_e32 v2, v148, v2
	v_add_f32_e32 v244, v149, v2
	v_cvt_pk_bf16_f32 v2, v240, v241
	v_cvt_pk_bf16_f32 v3, v242, v243
	v_mfma_f32_32x32x16_bf16 v[32:47], v[168:171], v[208:211], v[32:47]
	v_cvt_pk_bf16_f32 v4, v4, v5
	v_cvt_pk_bf16_f32 v5, v148, v149
	s_nop 0
	v_permlane32_swap_b32_e32 v2, v4
	v_permlane32_swap_b32_e32 v3, v5
	v_mfma_f32_32x32x16_bf16 v[16:31], v[168:171], v[212:215], v[16:31]
	ds_read_b64_tr_b16 v[148:149], v249 offset:0x2000
	ds_read_b64_tr_b16 v[150:151], v249 offset:0x2800
	ds_read_b64_tr_b16 v[164:165], v249 offset:0x2200
	ds_read_b64_tr_b16 v[166:167], v249 offset:0x2a00
	ds_read_b64_tr_b16 v[168:169], v249 offset:0x2400
	ds_read_b64_tr_b16 v[170:171], v249 offset:0x2c00
	ds_read_b64_tr_b16 v[172:173], v249 offset:0x2600
	ds_read_b64_tr_b16 v[174:175], v249 offset:0x2e00
	s_waitcnt lgkmcnt(8)
; #define SBAR() __builtin_amdgcn_sched_barrier(0)
; __device__ __forceinline__ float half_swap_sum(float v) { auto rr = __builtin_amdgcn_permlane32_swap(__float_as_uint(v), __float_as_uint(v), false, false); return __uint_as_float(rr[0]) + __uint_as_float(rr[1]); }
; #define LGKM_WAIT8() do { asm volatile("s_waitcnt lgkmcnt(8)" ::: "memory"); SBAR(); } while (0)
; #define LGKM_WAIT0() do { asm volatile("s_waitcnt lgkmcnt(0)" ::: "memory"); SBAR(); } while (0)
; #define EX4(P, B) do { _Pragma("unroll") for (int r_ = (B); r_ < (B) + 4; ++r_) { P[r_] = __builtin_amdgcn_exp2f(fmaf(P[r_], C, mnC)); ps += P[r_]; } } while (0)
; __device__ __forceinline__ void exp_pv256(f32x16 (&o)[8], f32x16& p0, f32x16& p1, int vb, float C, float mnC, float& ps) {
;     ...
;   vg4_read<2>(fa, vb); LGKM_WAIT8(); vg4_mma<1>(o, fb, pn); EX4(p1, 4); pa = pk4<0>(p1); SBAR();
;   vg4_read<2>(fb, vb + 16384); LGKM_WAIT8(); vg4_mma<0>(o, fa, pa); EX4(p1, 8); SBAR();
;   vg4_read<3>(fa, vb); LGKM_WAIT8(); vg4_mma<1>(o, fb, pa); EX4(p1, 12); pn = pk4<8>(p1); SBAR();
;   vg4_read<3>(fb, vb + 16384); LGKM_WAIT8(); vg4_mma<0>(o, fa, pn); SBAR();
;   LGKM_WAIT0(); vg4_mma<1>(o, fb, pn);
; template <int LD>
; __device__ __forceinline__ void attn256_body(const bf16_t* __restrict__ Qb, const bf16_t* __restrict__ Kh, const unsigned char* __restrict__ Vimg, int seq, char* lds, LAS unsigned char* ldsl,
;                                              f32x16 (&o)[8], float (&rli)[16]) {
;     ...
;     ps = half_swap_sum(ps);
;     l_reg = l_reg * alpha + ps;
;     asm volatile("s_waitcnt vmcnt(0)" ::: "memory"); __syncthreads();
;   }
	s_nop 0
	v_mfma_f32_32x32x16_bf16 v[128:143], v[2:5], v[6:9], v[128:143]
	v_fmamk_f32 v6, v152, 0x3e0293ee, v14
	v_exp_f32_e32 v208, v6
	v_fmamk_f32 v6, v153, 0x3e0293ee, v14
	v_exp_f32_e32 v209, v6
	v_fmamk_f32 v6, v154, 0x3e0293ee, v14
	v_exp_f32_e32 v210, v6
	v_fmamk_f32 v6, v155, 0x3e0293ee, v14
	v_mfma_f32_32x32x16_bf16 v[112:127], v[2:5], v[10:13], v[112:127]
	v_exp_f32_e32 v211, v6
	v_add_f32_e32 v6, v208, v244
	v_add_f32_e32 v6, v209, v6
	v_add_f32_e32 v6, v210, v6
	v_add_f32_e32 v212, v211, v6
	v_mfma_f32_32x32x16_bf16 v[96:111], v[2:5], v[144:147], v[96:111]
	v_mfma_f32_32x32x16_bf16 v[80:95], v[2:5], v[160:163], v[80:95]
	ds_read_b64_tr_b16 v[6:7], v15 offset:0x3000
	ds_read_b64_tr_b16 v[8:9], v15 offset:0x3800
	ds_read_b64_tr_b16 v[10:11], v15 offset:0x3200
	ds_read_b64_tr_b16 v[12:13], v15 offset:0x3a00
	ds_read_b64_tr_b16 v[144:145], v15 offset:0x3400
	ds_read_b64_tr_b16 v[146:147], v15 offset:0x3c00
	ds_read_b64_tr_b16 v[152:153], v15 offset:0x3600
	ds_read_b64_tr_b16 v[154:155], v15 offset:0x3e00
	s_waitcnt lgkmcnt(8)
	v_fmamk_f32 v15, v156, 0x3e0293ee, v14
	v_mfma_f32_32x32x16_bf16 v[64:79], v[2:5], v[148:151], v[64:79]
	v_exp_f32_e32 v15, v15
	v_fmamk_f32 v148, v157, 0x3e0293ee, v14
	v_exp_f32_e32 v150, v148
	v_fmamk_f32 v148, v158, 0x3e0293ee, v14
	v_exp_f32_e32 v151, v148
	v_fmac_f32_e32 v14, 0x3e0293ee, v159
	v_exp_f32_e32 v14, v14
	v_mfma_f32_32x32x16_bf16 v[48:63], v[2:5], v[164:167], v[48:63]
	v_add_f32_e32 v148, v15, v212
	v_add_f32_e32 v148, v150, v148
	v_add_f32_e32 v148, v151, v148
	v_add_f32_e32 v212, v14, v148
	v_cvt_pk_bf16_f32 v148, v208, v209
	v_cvt_pk_bf16_f32 v149, v210, v211
	v_cvt_pk_bf16_f32 v150, v15, v150
	v_mfma_f32_32x32x16_bf16 v[32:47], v[2:5], v[168:171], v[32:47]
	v_cvt_pk_bf16_f32 v151, v151, v14
	v_permlane32_swap_b32_e32 v148, v150
	v_permlane32_swap_b32_e32 v149, v151
	v_mfma_f32_32x32x16_bf16 v[16:31], v[2:5], v[172:175], v[16:31]
	ds_read_b64_tr_b16 v[2:3], v249 offset:0x3000
	ds_read_b64_tr_b16 v[4:5], v249 offset:0x3800
	ds_read_b64_tr_b16 v[156:157], v249 offset:0x3200
	ds_read_b64_tr_b16 v[158:159], v249 offset:0x3a00
	ds_read_b64_tr_b16 v[160:161], v249 offset:0x3400
	ds_read_b64_tr_b16 v[162:163], v249 offset:0x3c00
	ds_read_b64_tr_b16 v[164:165], v249 offset:0x3600
	ds_read_b64_tr_b16 v[166:167], v249 offset:0x3e00
	s_waitcnt lgkmcnt(8)
	s_nop 0
	v_mfma_f32_32x32x16_bf16 v[128:143], v[148:151], v[6:9], v[128:143]
	v_mfma_f32_32x32x16_bf16 v[112:127], v[148:151], v[10:13], v[112:127]
	v_mfma_f32_32x32x16_bf16 v[96:111], v[148:151], v[144:147], v[96:111]
	v_mfma_f32_32x32x16_bf16 v[80:95], v[148:151], v[152:155], v[80:95]
	s_waitcnt lgkmcnt(0)
	v_mfma_f32_32x32x16_bf16 v[64:79], v[148:151], v[2:5], v[64:79]
	v_mov_b32_e32 v2, v212
	s_nop 1
	v_permlane32_swap_b32_e32 v212, v2
	s_waitcnt vmcnt(0)
	v_add_f32_e32 v2, v212, v2
	v_fmac_f32_e32 v2, v239, v0
	v_lshl_add_u64 v[222:223], v[222:223], 0, s[30:31]
	v_mfma_f32_32x32x16_bf16 v[48:63], v[148:151], v[156:159], v[48:63]
	v_lshl_add_u64 v[224:225], v[224:225], 0, s[26:27]
	v_lshl_add_u64 v[226:227], v[226:227], 0, s[26:27]
	v_mov_b32_e32 v239, v2
	s_and_b32 s4, s45, 1
	s_cmpk_eq_i32 s45, 0xff
	s_cselect_b64 vcc, -1, 0
	s_cmpk_eq_i32 s45, 0x100
	s_waitcnt vmcnt(0) lgkmcnt(0)
	s_barrier
	v_mfma_f32_32x32x16_bf16 v[32:47], v[148:151], v[160:163], v[32:47]
	v_mfma_f32_32x32x16_bf16 v[16:31], v[148:151], v[164:167], v[16:31]
	s_cbranch_scc1 .LBB0_671
	s_cbranch_vccz .LBB0_662
	s_branch .LBB0_663

; __device__ __forceinline__ int crow(int r, int hi) { return (r & 3) + 8 * (r >> 2) + 4 * hi; }
; template <int LD>
; __device__ __forceinline__ void attn256_body(const bf16_t* __restrict__ Qb, const bf16_t* __restrict__ Kh, const unsigned char* __restrict__ Vimg, int seq, char* lds, LAS unsigned char* ldsl,
;                                              f32x16 (&o)[8], float (&rli)[16]) {
;     ...
;     if (__any(alpha < 1.f)) { if (hi == 0) al_l[r32] = alpha; asm volatile("s_waitcnt lgkmcnt(0)" ::: "memory");
; #pragma unroll
;       for (int d = 0; d < 8; ++d)
; #pragma unroll
;         for (int r = 0; r < 16; ++r) o[d][r] *= al_l[crow(r, hi)]; }
.LBB0_665:
	s_and_saveexec_b64 s[48:49], s[38:39]
	ds_write_b32 v219, v0 offset:128
	s_or_b64 exec, exec, s[48:49]
	s_waitcnt lgkmcnt(0)
	v_add_u32_e32 v2, s53, v220
	ds_read_b128 v[208:211], v2 offset:224
	ds_read_b128 v[10:13], v2 offset:192
	ds_read_b128 v[6:9], v2 offset:160
	ds_read_b128 v[2:5], v2 offset:128
	s_waitcnt lgkmcnt(0)
	v_pk_mul_f32 v[140:141], v[140:141], v[208:209]
	v_pk_mul_f32 v[136:137], v[136:137], v[10:11]
	v_pk_mul_f32 v[132:133], v[132:133], v[6:7]
	v_pk_mul_f32 v[142:143], v[142:143], v[210:211]
	v_pk_mul_f32 v[138:139], v[138:139], v[12:13]
	v_pk_mul_f32 v[134:135], v[134:135], v[8:9]
	v_pk_mul_f32 v[130:131], v[130:131], v[4:5]
	v_pk_mul_f32 v[128:129], v[128:129], v[2:3]
	v_pk_mul_f32 v[124:125], v[124:125], v[208:209]
	v_pk_mul_f32 v[120:121], v[120:121], v[10:11]
	v_pk_mul_f32 v[116:117], v[116:117], v[6:7]
	v_pk_mul_f32 v[126:127], v[126:127], v[210:211]
	v_pk_mul_f32 v[122:123], v[122:123], v[12:13]
	v_pk_mul_f32 v[118:119], v[118:119], v[8:9]
	v_pk_mul_f32 v[114:115], v[114:115], v[4:5]
	v_pk_mul_f32 v[112:113], v[112:113], v[2:3]
	v_pk_mul_f32 v[108:109], v[108:109], v[208:209]
	v_pk_mul_f32 v[104:105], v[104:105], v[10:11]
	v_pk_mul_f32 v[100:101], v[100:101], v[6:7]
	v_pk_mul_f32 v[110:111], v[110:111], v[210:211]
	v_pk_mul_f32 v[106:107], v[106:107], v[12:13]
	v_pk_mul_f32 v[102:103], v[102:103], v[8:9]
	v_pk_mul_f32 v[98:99], v[98:99], v[4:5]
	v_pk_mul_f32 v[96:97], v[96:97], v[2:3]
	v_pk_mul_f32 v[92:93], v[92:93], v[208:209]
	v_pk_mul_f32 v[88:89], v[88:89], v[10:11]
	v_pk_mul_f32 v[84:85], v[84:85], v[6:7]
	v_pk_mul_f32 v[94:95], v[94:95], v[210:211]
	v_pk_mul_f32 v[90:91], v[90:91], v[12:13]
	v_pk_mul_f32 v[86:87], v[86:87], v[8:9]
	v_pk_mul_f32 v[82:83], v[82:83], v[4:5]
	v_pk_mul_f32 v[80:81], v[80:81], v[2:3]
	v_pk_mul_f32 v[76:77], v[76:77], v[208:209]
	v_pk_mul_f32 v[72:73], v[72:73], v[10:11]
	v_pk_mul_f32 v[68:69], v[68:69], v[6:7]
	v_pk_mul_f32 v[78:79], v[78:79], v[210:211]
	v_pk_mul_f32 v[74:75], v[74:75], v[12:13]
	v_pk_mul_f32 v[70:71], v[70:71], v[8:9]
	v_pk_mul_f32 v[66:67], v[66:67], v[4:5]
	v_pk_mul_f32 v[64:65], v[64:65], v[2:3]
	v_pk_mul_f32 v[60:61], v[60:61], v[208:209]
	v_pk_mul_f32 v[56:57], v[56:57], v[10:11]
	v_pk_mul_f32 v[52:53], v[52:53], v[6:7]
	v_pk_mul_f32 v[62:63], v[62:63], v[210:211]
	v_pk_mul_f32 v[58:59], v[58:59], v[12:13]
	v_pk_mul_f32 v[54:55], v[54:55], v[8:9]
	v_pk_mul_f32 v[50:51], v[50:51], v[4:5]
	v_pk_mul_f32 v[48:49], v[48:49], v[2:3]
	v_pk_mul_f32 v[44:45], v[44:45], v[208:209]
	v_pk_mul_f32 v[40:41], v[40:41], v[10:11]
	v_pk_mul_f32 v[36:37], v[36:37], v[6:7]
	v_pk_mul_f32 v[46:47], v[46:47], v[210:211]
	v_pk_mul_f32 v[42:43], v[42:43], v[12:13]
	v_pk_mul_f32 v[38:39], v[38:39], v[8:9]
	v_pk_mul_f32 v[34:35], v[34:35], v[4:5]
	v_pk_mul_f32 v[32:33], v[32:33], v[2:3]
	v_pk_mul_f32 v[28:29], v[28:29], v[208:209]
	v_pk_mul_f32 v[24:25], v[24:25], v[10:11]
	v_pk_mul_f32 v[20:21], v[20:21], v[6:7]
	v_pk_mul_f32 v[30:31], v[30:31], v[210:211]
	v_pk_mul_f32 v[26:27], v[26:27], v[12:13]
	v_pk_mul_f32 v[22:23], v[22:23], v[8:9]
	v_pk_mul_f32 v[18:19], v[18:19], v[4:5]
	v_pk_mul_f32 v[16:17], v[16:17], v[2:3]
	s_branch .LBB0_668

; #define SBAR() __builtin_amdgcn_sched_barrier(0)
; __device__ __forceinline__ float qkt_deep(f32x16& p0, f32x16& p1, const int (&ka)[4], const bf16x8 (&qr)[8]) {
;     ...
;   QD_RD0(0); QD_RD0(1); QD_RD0(2); QD_RD0(3); QD_RD0(4); QD_RD0(5); QD_RD0(6); QD_RD0(7);
;   QK_WAIT(7); QD_MM0(0); SBAR(); QD_RD1(0);
;   QK_WAIT(7); QD_MM0(1); SBAR(); QD_RD1(1);
;   QK_WAIT(7); QD_MM0(2); SBAR(); QD_RD1(2);
;   QK_WAIT(7); QD_MM0(3); SBAR(); QD_RD1(3);
;   QK_WAIT(7); QD_MM0(4); SBAR(); QD_RD1(4);
;   QK_WAIT(7); QD_MM0(5); SBAR(); QD_RD1(5);
;   QK_WAIT(7); QD_MM0(6); SBAR(); QD_RD1(6);
;   QK_WAIT(7); QD_MM0(7); SBAR(); QD_RD1(7);
;   QK_WAIT(7); QD_MM1(0); pm = fmaxf(p0[0], p0[1]); SBAR();
;   QK_WAIT(6); QD_MM1(1); pm = fmaxf(fmaxf(pm, p0[2]), p0[3]); SBAR();
;   QK_WAIT(5); QD_MM1(2); pm = fmaxf(fmaxf(pm, p0[4]), p0[5]); SBAR();
;   QK_WAIT(4); QD_MM1(3); pm = fmaxf(fmaxf(pm, p0[6]), p0[7]); SBAR();
;   QK_WAIT(3); QD_MM1(4); pm = fmaxf(fmaxf(pm, p0[8]), p0[9]); SBAR();
;   QK_WAIT(2); QD_MM1(5); pm = fmaxf(fmaxf(pm, p0[10]), p0[11]); SBAR();
;   QK_WAIT(1); QD_MM1(6); pm = fmaxf(fmaxf(pm, p0[12]), p0[13]); SBAR();
;   QK_WAIT(0); QD_MM1(7); pm = fmaxf(fmaxf(pm, p0[14]), p0[15]);
;   return pm;
; }
; template <int LD>
; __device__ __forceinline__ void attn256_body(const bf16_t* __restrict__ Qb, const bf16_t* __restrict__ Kh, const unsigned char* __restrict__ Vimg, int seq, char* lds, LAS unsigned char* ldsl,
;                                              f32x16 (&o)[8], float (&rli)[16]) {
;     ...
;   for (int j = 0; j < NT; ++j) {
;     const int cur = j & 1;
;     if (j + 1 < NT) { if (cur) A2_DMA(0, (j + 1) * 64); else A2_DMA(1, (j + 1) * 64); }
;     f32x16 p0 = f32x16{}, p1 = f32x16{}; float pmax;
;     { int ka[4];
; #pragma unroll
;       for (int q = 0; q < 4; ++q) ka[q] = kbase + cur * A2_STAGE + (((2 * q + hi) ^ (r32 & 7)) << 4);
;       pmax = qkt_deep(p0, p1, ka, qr); }
; #pragma unroll
;     for (int r = 0; r < 16; ++r) pmax = fmaxf(pmax, p1[r]);
;     pmax = half_swap_max(pmax);
;     float mn, alpha;
;     if (__builtin_expect(__all(pmax - m_reg <= ATT_THR / ATT_SCALE), 1)) { mn = m_reg; alpha = 1.f; }
;     else { mn = fmaxf(m_reg, pmax); alpha = __builtin_amdgcn_exp2f((m_reg - mn) * C); m_reg = mn; }
;     const float mnC = -mn * C; float ps;
;     if (__any(alpha < 1.f)) { if (hi == 0) al_l[r32] = alpha; asm volatile("s_waitcnt lgkmcnt(0)" ::: "memory");
.LBB0_677:
	s_mul_i32 s4, s4, 0xc000
	s_waitcnt lgkmcnt(0)
	v_add_u32_e32 v0, s4, v221
	v_add_u32_e32 v248, v0, v233
	v_add_u32_e32 v249, v0, v234
	v_add_u32_e32 v250, v0, v235
	v_add_u32_e32 v0, v0, v236
	ds_read_b128 v[130:133], v248 offset:0
	ds_read_b128 v[134:137], v249 offset:0
	ds_read_b128 v[138:141], v250 offset:0
	ds_read_b128 v[142:145], v0 offset:0
	ds_read_b128 v[194:197], v248 offset:0x80
	ds_read_b128 v[198:201], v249 offset:0x80
	ds_read_b128 v[202:205], v250 offset:0x80
	ds_read_b128 v[206:209], v0 offset:0x80
	s_waitcnt lgkmcnt(7)
	s_nop 0
	v_mfma_f32_32x32x16_bf16 v[146:161], v[130:133], v[162:165], 0
	ds_read_b128 v[130:133], v248 offset:0x2000
	s_waitcnt lgkmcnt(7)
	s_nop 0
	v_mfma_f32_32x32x16_bf16 v[146:161], v[134:137], v[166:169], v[146:161]
	ds_read_b128 v[212:215], v249 offset:0x2000
	s_waitcnt lgkmcnt(7)
	s_nop 0
	v_mfma_f32_32x32x16_bf16 v[146:161], v[138:141], v[170:173], v[146:161]
	ds_read_b128 v[240:243], v250 offset:0x2000
	s_waitcnt lgkmcnt(7)
	s_nop 0
	v_mfma_f32_32x32x16_bf16 v[146:161], v[142:145], v[174:177], v[146:161]
	ds_read_b128 v[244:247], v0 offset:0x2000
	s_waitcnt lgkmcnt(7)
	s_nop 0
	v_mfma_f32_32x32x16_bf16 v[146:161], v[194:197], v[178:181], v[146:161]
	ds_read_b128 v[194:197], v248 offset:0x2080
	s_waitcnt lgkmcnt(7)
	s_nop 0
	v_mfma_f32_32x32x16_bf16 v[146:161], v[198:201], v[182:185], v[146:161]
	ds_read_b128 v[198:201], v249 offset:0x2080
	s_waitcnt lgkmcnt(7)
	s_nop 0
	v_mfma_f32_32x32x16_bf16 v[146:161], v[202:205], v[186:189], v[146:161]
	ds_read_b128 v[202:205], v250 offset:0x2080
	s_waitcnt lgkmcnt(7)
	s_nop 0
	v_mfma_f32_32x32x16_bf16 v[146:161], v[206:209], v[190:193], v[146:161]
	ds_read_b128 v[206:209], v0 offset:0x2080
	s_waitcnt lgkmcnt(7)
	s_nop 11
	v_max_f32_e32 v0, v147, v147
	v_max_f32_e32 v248, v146, v146
	v_mfma_f32_32x32x16_bf16 v[130:145], v[130:133], v[162:165], 0
	v_max_f32_e32 v0, v248, v0
	s_waitcnt lgkmcnt(6)
	s_nop 0
	v_mfma_f32_32x32x16_bf16 v[130:145], v[212:215], v[166:169], v[130:145]
	v_max3_f32 v0, v0, v148, v149
	s_waitcnt lgkmcnt(5)
	s_nop 0
	v_mfma_f32_32x32x16_bf16 v[130:145], v[240:243], v[170:173], v[130:145]
	v_max3_f32 v0, v0, v150, v151
	s_waitcnt lgkmcnt(4)
	s_nop 0
	v_mfma_f32_32x32x16_bf16 v[130:145], v[244:247], v[174:177], v[130:145]
	v_max3_f32 v0, v0, v152, v153
	s_waitcnt lgkmcnt(3)
	s_nop 0
	v_mfma_f32_32x32x16_bf16 v[130:145], v[194:197], v[178:181], v[130:145]
	v_max3_f32 v0, v0, v154, v155
	s_waitcnt lgkmcnt(2)
	s_nop 0
	v_mfma_f32_32x32x16_bf16 v[130:145], v[198:201], v[182:185], v[130:145]
	v_max3_f32 v0, v0, v156, v157
	s_waitcnt lgkmcnt(1)
	s_nop 0
	v_mfma_f32_32x32x16_bf16 v[130:145], v[202:205], v[186:189], v[130:145]
	v_max3_f32 v0, v0, v158, v159
	s_waitcnt lgkmcnt(0)
	s_nop 0
	v_mfma_f32_32x32x16_bf16 v[130:145], v[206:209], v[190:193], v[130:145]
	v_max3_f32 v0, v0, v160, v161
	s_nop 10
	v_max3_f32 v0, v0, v130, v131
	v_max3_f32 v0, v0, v132, v133
	v_max3_f32 v0, v0, v134, v135
	v_max3_f32 v0, v0, v136, v137
	v_max3_f32 v0, v0, v138, v139
	v_max3_f32 v0, v0, v140, v141
	v_max3_f32 v0, v0, v142, v143
	v_max3_f32 v0, v0, v144, v145
	v_mov_b32_e32 v194, v0
	s_nop 1
	v_permlane32_swap_b32_e32 v0, v194
	v_max_f32_e32 v194, v194, v194
	v_max_f32_e32 v0, v0, v0
	v_max_f32_e32 v194, v0, v194
	v_sub_f32_e32 v0, v194, v238
	v_cmp_ge_f32_e32 vcc, s93, v0
	s_cmp_eq_u64 vcc, exec
	v_mov_b32_e32 v0, 1.0
	s_cbranch_scc0 .LBB0_684
.LBB0_682:
	v_mul_f32_e32 v248, 0xbe0293ee, v238
	v_fmamk_f32 v146, v146, 0x3e0293ee, v248
	v_exp_f32_e32 v146, v146
	v_fmamk_f32 v147, v147, 0x3e0293ee, v248
	v_exp_f32_e32 v147, v147
	v_fmamk_f32 v148, v148, 0x3e0293ee, v248
	v_exp_f32_e32 v148, v148
	v_fmamk_f32 v149, v149, 0x3e0293ee, v248
	v_exp_f32_e32 v149, v149
	v_fmamk_f32 v150, v150, 0x3e0293ee, v248
	v_add_f32_e32 v194, 0, v146
	v_exp_f32_e32 v150, v150
	v_fmamk_f32 v151, v151, 0x3e0293ee, v248
	v_add_f32_e32 v194, v147, v194
	v_exp_f32_e32 v151, v151
	v_fmamk_f32 v152, v152, 0x3e0293ee, v248
	v_add_f32_e32 v194, v148, v194
	v_exp_f32_e32 v152, v152
	v_fmamk_f32 v153, v153, 0x3e0293ee, v248
	v_add_f32_e32 v194, v149, v194
	v_exp_f32_e32 v153, v153
	v_add_f32_e32 v194, v150, v194
	v_cvt_pk_bf16_f32 v146, v146, v147
	v_cvt_pk_bf16_f32 v147, v148, v149
	v_cvt_pk_bf16_f32 v148, v150, v151
	v_cvt_pk_bf16_f32 v149, v152, v153
	s_waitcnt lgkmcnt(0)
	v_add_f32_e32 v194, v151, v194
	s_add_i32 s34, s34, 1
	v_add_f32_e32 v194, v152, v194
	v_add_u32_e32 v249, s4, v237
	v_add_f32_e32 v250, v153, v194
	v_permlane32_swap_b32_e32 v146, v148
	v_permlane32_swap_b32_e32 v147, v149
	ds_read_b64_tr_b16 v[150:151], v249 offset:0
	ds_read_b64_tr_b16 v[152:153], v249 offset:0x800
	ds_read_b64_tr_b16 v[194:195], v249 offset:0x200
	ds_read_b64_tr_b16 v[196:197], v249 offset:0xa00
	ds_read_b64_tr_b16 v[198:199], v249 offset:0x400
	ds_read_b64_tr_b16 v[200:201], v249 offset:0xc00
	ds_read_b64_tr_b16 v[202:203], v249 offset:0x600
	ds_read_b64_tr_b16 v[204:205], v249 offset:0xe00
	v_add_u32_e32 v251, 0x4000, v249
	ds_read_b64_tr_b16 v[206:207], v251 offset:0
	ds_read_b64_tr_b16 v[208:209], v251 offset:0x800
	ds_read_b64_tr_b16 v[212:213], v251 offset:0x200
	ds_read_b64_tr_b16 v[214:215], v251 offset:0xa00
	ds_read_b64_tr_b16 v[240:241], v251 offset:0x400
	ds_read_b64_tr_b16 v[242:243], v251 offset:0xc00
	ds_read_b64_tr_b16 v[244:245], v251 offset:0x600
	ds_read_b64_tr_b16 v[246:247], v251 offset:0xe00
	s_waitcnt lgkmcnt(8)
; #define SBAR() __builtin_amdgcn_sched_barrier(0)
; #define LGKM_WAIT8() do { asm volatile("s_waitcnt lgkmcnt(8)" ::: "memory"); SBAR(); } while (0)
; #define LGKM_WAIT0() do { asm volatile("s_waitcnt lgkmcnt(0)" ::: "memory"); SBAR(); } while (0)
; #define EX4(P, B) do { _Pragma("unroll") for (int r_ = (B); r_ < (B) + 4; ++r_) { P[r_] = __builtin_amdgcn_exp2f(fmaf(P[r_], C, mnC)); ps += P[r_]; } } while (0)
; __device__ __forceinline__ void exp_pv256(f32x16 (&o)[8], f32x16& p0, f32x16& p1, int vb, float C, float mnC, float& ps) {
;   VG4 fa, fb; bf16x8 pa, pn;
;   ps = 0.f;
;   EX4(p0, 0); EX4(p0, 4); pa = pk4<0>(p0);
;   asm volatile("s_waitcnt lgkmcnt(0)" ::: "memory"); SBAR();
;   vg4_read<0>(fa, vb); vg4_read<0>(fb, vb + 16384);
;   LGKM_WAIT8(); vg4_mma<0>(o, fa, pa); EX4(p0, 8); SBAR();
;   vg4_read<1>(fa, vb); LGKM_WAIT8(); vg4_mma<1>(o, fb, pa); EX4(p0, 12); pn = pk4<8>(p0); SBAR();
;   vg4_read<1>(fb, vb + 16384); LGKM_WAIT8(); vg4_mma<0>(o, fa, pn); EX4(p1, 0); SBAR();
;   vg4_read<2>(fa, vb); LGKM_WAIT8(); vg4_mma<1>(o, fb, pn); EX4(p1, 4); pa = pk4<0>(p1); SBAR();
;   vg4_read<2>(fb, vb + 16384); LGKM_WAIT8(); vg4_mma<0>(o, fa, pa); EX4(p1, 8); SBAR();
;   vg4_read<3>(fa, vb); LGKM_WAIT8(); vg4_mma<1>(o, fb, pa); EX4(p1, 12); pn = pk4<8>(p1); SBAR();
;   vg4_read<3>(fb, vb + 16384); LGKM_WAIT8(); vg4_mma<0>(o, fa, pn); SBAR();
;   LGKM_WAIT0(); vg4_mma<1>(o, fb, pn);
	s_nop 0
	v_mfma_f32_32x32x16_bf16 v[2:17], v[146:149], v[150:153], v[2:17]
	v_fmamk_f32 v150, v154, 0x3e0293ee, v248
	v_exp_f32_e32 v252, v150
	v_fmamk_f32 v150, v155, 0x3e0293ee, v248
	v_exp_f32_e32 v231, v150
	v_fmamk_f32 v150, v156, 0x3e0293ee, v248
	v_exp_f32_e32 v232, v150
	v_fmamk_f32 v150, v157, 0x3e0293ee, v248
	v_mfma_f32_32x32x16_bf16 v[18:33], v[146:149], v[194:197], v[18:33]
	v_exp_f32_e32 v216, v150
	v_add_f32_e32 v150, v252, v250
	v_add_f32_e32 v150, v231, v150
	v_add_f32_e32 v150, v232, v150
	v_add_f32_e32 v217, v216, v150
	v_mfma_f32_32x32x16_bf16 v[34:49], v[146:149], v[198:201], v[34:49]
	v_mfma_f32_32x32x16_bf16 v[50:65], v[146:149], v[202:205], v[50:65]
	ds_read_b64_tr_b16 v[150:151], v249 offset:0x1000
	ds_read_b64_tr_b16 v[152:153], v249 offset:0x1800
	ds_read_b64_tr_b16 v[154:155], v249 offset:0x1200
	ds_read_b64_tr_b16 v[156:157], v249 offset:0x1a00
	ds_read_b64_tr_b16 v[194:195], v249 offset:0x1400
	ds_read_b64_tr_b16 v[196:197], v249 offset:0x1c00
	ds_read_b64_tr_b16 v[198:199], v249 offset:0x1600
	ds_read_b64_tr_b16 v[200:201], v249 offset:0x1e00
	s_waitcnt lgkmcnt(8)
	v_fmamk_f32 v158, v158, 0x3e0293ee, v248
	v_mfma_f32_32x32x16_bf16 v[66:81], v[146:149], v[206:209], v[66:81]
	v_exp_f32_e32 v202, v158
	v_fmamk_f32 v158, v159, 0x3e0293ee, v248
	v_exp_f32_e32 v203, v158
	v_fmamk_f32 v158, v160, 0x3e0293ee, v248
	v_exp_f32_e32 v204, v158
	v_fmamk_f32 v158, v161, 0x3e0293ee, v248
	v_exp_f32_e32 v161, v158
	v_mfma_f32_32x32x16_bf16 v[82:97], v[146:149], v[212:215], v[82:97]
	v_add_f32_e32 v158, v202, v217
	v_add_f32_e32 v158, v203, v158
	v_add_f32_e32 v158, v204, v158
	v_add_f32_e32 v217, v161, v158
	v_cvt_pk_bf16_f32 v158, v252, v231
	v_cvt_pk_bf16_f32 v159, v232, v216
	v_cvt_pk_bf16_f32 v160, v202, v203
	v_mfma_f32_32x32x16_bf16 v[98:113], v[146:149], v[240:243], v[98:113]
	v_cvt_pk_bf16_f32 v161, v204, v161
	v_permlane32_swap_b32_e32 v158, v160
	v_permlane32_swap_b32_e32 v159, v161
	v_mfma_f32_32x32x16_bf16 v[114:129], v[146:149], v[244:247], v[114:129]
	ds_read_b64_tr_b16 v[146:147], v251 offset:0x1000
	ds_read_b64_tr_b16 v[148:149], v251 offset:0x1800
	ds_read_b64_tr_b16 v[202:203], v251 offset:0x1200
	ds_read_b64_tr_b16 v[204:205], v251 offset:0x1a00
	ds_read_b64_tr_b16 v[206:207], v251 offset:0x1400
	ds_read_b64_tr_b16 v[208:209], v251 offset:0x1c00
	ds_read_b64_tr_b16 v[212:213], v251 offset:0x1600
	ds_read_b64_tr_b16 v[214:215], v251 offset:0x1e00
	s_waitcnt lgkmcnt(8)
	s_nop 0
	v_mfma_f32_32x32x16_bf16 v[2:17], v[158:161], v[150:153], v[2:17]
	v_fmamk_f32 v130, v130, 0x3e0293ee, v248
	v_exp_f32_e32 v216, v130
	v_fmamk_f32 v130, v131, 0x3e0293ee, v248
	v_exp_f32_e32 v231, v130
	v_fmamk_f32 v130, v132, 0x3e0293ee, v248
	v_exp_f32_e32 v232, v130
	v_fmamk_f32 v130, v133, 0x3e0293ee, v248
	v_mfma_f32_32x32x16_bf16 v[18:33], v[158:161], v[154:157], v[18:33]
	v_exp_f32_e32 v240, v130
	v_add_f32_e32 v130, v216, v217
	v_add_f32_e32 v130, v231, v130
	v_add_f32_e32 v130, v232, v130
	v_add_f32_e32 v217, v240, v130
	v_mfma_f32_32x32x16_bf16 v[34:49], v[158:161], v[194:197], v[34:49]
	v_mfma_f32_32x32x16_bf16 v[50:65], v[158:161], v[198:201], v[50:65]
	ds_read_b64_tr_b16 v[130:131], v249 offset:0x2000
	ds_read_b64_tr_b16 v[132:133], v249 offset:0x2800
	ds_read_b64_tr_b16 v[150:151], v249 offset:0x2200
	ds_read_b64_tr_b16 v[152:153], v249 offset:0x2a00
	ds_read_b64_tr_b16 v[154:155], v249 offset:0x2400
	ds_read_b64_tr_b16 v[156:157], v249 offset:0x2c00
	ds_read_b64_tr_b16 v[194:195], v249 offset:0x2600
	ds_read_b64_tr_b16 v[196:197], v249 offset:0x2e00
	s_waitcnt lgkmcnt(8)
	v_fmamk_f32 v134, v134, 0x3e0293ee, v248
	v_mfma_f32_32x32x16_bf16 v[66:81], v[158:161], v[146:149], v[66:81]
	v_exp_f32_e32 v146, v134
	v_fmamk_f32 v134, v135, 0x3e0293ee, v248
	v_exp_f32_e32 v147, v134
	v_fmamk_f32 v134, v136, 0x3e0293ee, v248
	v_exp_f32_e32 v148, v134
	v_fmamk_f32 v134, v137, 0x3e0293ee, v248
	v_exp_f32_e32 v137, v134
	v_mfma_f32_32x32x16_bf16 v[82:97], v[158:161], v[202:205], v[82:97]
	v_add_f32_e32 v134, v146, v217
	v_add_f32_e32 v134, v147, v134
	v_add_f32_e32 v134, v148, v134
	v_add_f32_e32 v217, v137, v134
	v_cvt_pk_bf16_f32 v134, v216, v231
	v_cvt_pk_bf16_f32 v135, v232, v240
	v_cvt_pk_bf16_f32 v136, v146, v147
	v_mfma_f32_32x32x16_bf16 v[98:113], v[158:161], v[206:209], v[98:113]
	v_cvt_pk_bf16_f32 v137, v148, v137
	v_permlane32_swap_b32_e32 v134, v136
	v_permlane32_swap_b32_e32 v135, v137
	v_mfma_f32_32x32x16_bf16 v[114:129], v[158:161], v[212:215], v[114:129]
	ds_read_b64_tr_b16 v[146:147], v251 offset:0x2000
	ds_read_b64_tr_b16 v[148:149], v251 offset:0x2800
	ds_read_b64_tr_b16 v[158:159], v251 offset:0x2200
	ds_read_b64_tr_b16 v[160:161], v251 offset:0x2a00
	ds_read_b64_tr_b16 v[198:199], v251 offset:0x2400
	ds_read_b64_tr_b16 v[200:201], v251 offset:0x2c00
	ds_read_b64_tr_b16 v[202:203], v251 offset:0x2600
	ds_read_b64_tr_b16 v[204:205], v251 offset:0x2e00
	s_waitcnt lgkmcnt(8)
; #define SBAR() __builtin_amdgcn_sched_barrier(0)
; __device__ __forceinline__ float half_swap_sum(float v) { auto rr = __builtin_amdgcn_permlane32_swap(__float_as_uint(v), __float_as_uint(v), false, false); return __uint_as_float(rr[0]) + __uint_as_float(rr[1]); }
; #define LGKM_WAIT8() do { asm volatile("s_waitcnt lgkmcnt(8)" ::: "memory"); SBAR(); } while (0)
; #define LGKM_WAIT0() do { asm volatile("s_waitcnt lgkmcnt(0)" ::: "memory"); SBAR(); } while (0)
; #define EX4(P, B) do { _Pragma("unroll") for (int r_ = (B); r_ < (B) + 4; ++r_) { P[r_] = __builtin_amdgcn_exp2f(fmaf(P[r_], C, mnC)); ps += P[r_]; } } while (0)
; __device__ __forceinline__ void exp_pv256(f32x16 (&o)[8], f32x16& p0, f32x16& p1, int vb, float C, float mnC, float& ps) {
;     ...
;   vg4_read<2>(fa, vb); LGKM_WAIT8(); vg4_mma<1>(o, fb, pn); EX4(p1, 4); pa = pk4<0>(p1); SBAR();
;   vg4_read<2>(fb, vb + 16384); LGKM_WAIT8(); vg4_mma<0>(o, fa, pa); EX4(p1, 8); SBAR();
;   vg4_read<3>(fa, vb); LGKM_WAIT8(); vg4_mma<1>(o, fb, pa); EX4(p1, 12); pn = pk4<8>(p1); SBAR();
;   vg4_read<3>(fb, vb + 16384); LGKM_WAIT8(); vg4_mma<0>(o, fa, pn); SBAR();
;   LGKM_WAIT0(); vg4_mma<1>(o, fb, pn);
; template <int LD>
; __device__ __forceinline__ void attn256_body(const bf16_t* __restrict__ Qb, const bf16_t* __restrict__ Kh, const unsigned char* __restrict__ Vimg, int seq, char* lds, LAS unsigned char* ldsl,
;                                              f32x16 (&o)[8], float (&rli)[16]) {
;     ...
;     ps = half_swap_sum(ps);
;     l_reg = l_reg * alpha + ps;
;     asm volatile("s_waitcnt vmcnt(0)" ::: "memory"); __syncthreads();
;   }
	s_nop 0
	v_mfma_f32_32x32x16_bf16 v[2:17], v[134:137], v[130:133], v[2:17]
	v_fmamk_f32 v130, v138, 0x3e0293ee, v248
	v_exp_f32_e32 v206, v130
	v_fmamk_f32 v130, v139, 0x3e0293ee, v248
	v_exp_f32_e32 v207, v130
	v_fmamk_f32 v130, v140, 0x3e0293ee, v248
	v_exp_f32_e32 v208, v130
	v_fmamk_f32 v130, v141, 0x3e0293ee, v248
	v_mfma_f32_32x32x16_bf16 v[18:33], v[134:137], v[150:153], v[18:33]
	v_exp_f32_e32 v209, v130
	v_add_f32_e32 v130, v206, v217
	v_add_f32_e32 v130, v207, v130
	v_add_f32_e32 v130, v208, v130
	v_add_f32_e32 v212, v209, v130
	v_mfma_f32_32x32x16_bf16 v[34:49], v[134:137], v[154:157], v[34:49]
	v_mfma_f32_32x32x16_bf16 v[50:65], v[134:137], v[194:197], v[50:65]
	ds_read_b64_tr_b16 v[130:131], v249 offset:0x3000
	ds_read_b64_tr_b16 v[132:133], v249 offset:0x3800
	ds_read_b64_tr_b16 v[138:139], v249 offset:0x3200
	ds_read_b64_tr_b16 v[140:141], v249 offset:0x3a00
	ds_read_b64_tr_b16 v[150:151], v249 offset:0x3400
	ds_read_b64_tr_b16 v[152:153], v249 offset:0x3c00
	ds_read_b64_tr_b16 v[154:155], v249 offset:0x3600
	ds_read_b64_tr_b16 v[156:157], v249 offset:0x3e00
	s_waitcnt lgkmcnt(8)
	v_fmamk_f32 v142, v142, 0x3e0293ee, v248
	v_mfma_f32_32x32x16_bf16 v[66:81], v[134:137], v[146:149], v[66:81]
	v_exp_f32_e32 v146, v142
	v_fmamk_f32 v142, v143, 0x3e0293ee, v248
	v_exp_f32_e32 v147, v142
	v_fmamk_f32 v142, v144, 0x3e0293ee, v248
	v_exp_f32_e32 v148, v142
	v_fmac_f32_e32 v248, 0x3e0293ee, v145
	v_exp_f32_e32 v145, v248
	v_mfma_f32_32x32x16_bf16 v[82:97], v[134:137], v[158:161], v[82:97]
	v_add_f32_e32 v142, v146, v212
	v_add_f32_e32 v142, v147, v142
	v_add_f32_e32 v142, v148, v142
	v_add_f32_e32 v212, v145, v142
	v_cvt_pk_bf16_f32 v142, v206, v207
	v_cvt_pk_bf16_f32 v143, v208, v209
	v_cvt_pk_bf16_f32 v144, v146, v147
	v_mfma_f32_32x32x16_bf16 v[98:113], v[134:137], v[198:201], v[98:113]
	v_cvt_pk_bf16_f32 v145, v148, v145
	v_permlane32_swap_b32_e32 v142, v144
	v_permlane32_swap_b32_e32 v143, v145
	v_mfma_f32_32x32x16_bf16 v[114:129], v[134:137], v[202:205], v[114:129]
	ds_read_b64_tr_b16 v[134:135], v251 offset:0x3000
	ds_read_b64_tr_b16 v[136:137], v251 offset:0x3800
	ds_read_b64_tr_b16 v[146:147], v251 offset:0x3200
	ds_read_b64_tr_b16 v[148:149], v251 offset:0x3a00
	ds_read_b64_tr_b16 v[158:159], v251 offset:0x3400
	ds_read_b64_tr_b16 v[160:161], v251 offset:0x3c00
	ds_read_b64_tr_b16 v[194:195], v251 offset:0x3600
	ds_read_b64_tr_b16 v[196:197], v251 offset:0x3e00
	s_waitcnt lgkmcnt(8)
	s_nop 0
	v_mfma_f32_32x32x16_bf16 v[2:17], v[142:145], v[130:133], v[2:17]
	v_mfma_f32_32x32x16_bf16 v[18:33], v[142:145], v[138:141], v[18:33]
	v_mfma_f32_32x32x16_bf16 v[34:49], v[142:145], v[150:153], v[34:49]
	v_mfma_f32_32x32x16_bf16 v[50:65], v[142:145], v[154:157], v[50:65]
	s_waitcnt lgkmcnt(0)
	v_mfma_f32_32x32x16_bf16 v[66:81], v[142:145], v[134:137], v[66:81]
	v_mov_b32_e32 v130, v212
	s_nop 1
	v_permlane32_swap_b32_e32 v212, v130
	s_waitcnt vmcnt(0)
	v_add_f32_e32 v130, v212, v130
	v_fmac_f32_e32 v130, v239, v0
	v_lshl_add_u64 v[222:223], v[222:223], 0, s[30:31]
	v_mfma_f32_32x32x16_bf16 v[82:97], v[142:145], v[146:149], v[82:97]
	v_lshl_add_u64 v[224:225], v[224:225], 0, s[26:27]
	v_lshl_add_u64 v[226:227], v[226:227], 0, s[26:27]
	v_mov_b32_e32 v239, v130
	s_and_b32 s4, s34, 1
	s_cmpk_eq_i32 s34, 0xff
	s_cselect_b64 vcc, -1, 0
	s_cmpk_eq_i32 s34, 0x100
	s_waitcnt vmcnt(0) lgkmcnt(0)
	s_barrier
	v_mfma_f32_32x32x16_bf16 v[98:113], v[142:145], v[158:161], v[98:113]
	v_mfma_f32_32x32x16_bf16 v[114:129], v[142:145], v[194:197], v[114:129]
	s_cbranch_scc1 .LBB0_685
	s_cbranch_vccz .LBB0_676
	s_branch .LBB0_677

; __device__ __forceinline__ int crow(int r, int hi) { return (r & 3) + 8 * (r >> 2) + 4 * hi; }
; template <int LD>
; __device__ __forceinline__ void attn256_body(const bf16_t* __restrict__ Qb, const bf16_t* __restrict__ Kh, const unsigned char* __restrict__ Vimg, int seq, char* lds, LAS unsigned char* ldsl,
;                                              f32x16 (&o)[8], float (&rli)[16]) {
;     ...
;     if (__any(alpha < 1.f)) { if (hi == 0) al_l[r32] = alpha; asm volatile("s_waitcnt lgkmcnt(0)" ::: "memory");
; #pragma unroll
;       for (int d = 0; d < 8; ++d)
; #pragma unroll
;         for (int r = 0; r < 16; ++r) o[d][r] *= al_l[crow(r, hi)]; }
.LBB0_679:
	s_and_saveexec_b64 s[12:13], s[38:39]
	ds_write_b32 v219, v0 offset:128
	s_or_b64 exec, exec, s[12:13]
	s_waitcnt lgkmcnt(0)
	v_add_u32_e32 v194, s29, v220
	ds_read_b128 v[206:209], v194 offset:224
	ds_read_b128 v[202:205], v194 offset:192
	ds_read_b128 v[198:201], v194 offset:160
	ds_read_b128 v[194:197], v194 offset:128
	s_waitcnt lgkmcnt(0)
	v_pk_mul_f32 v[14:15], v[14:15], v[206:207]
	v_pk_mul_f32 v[10:11], v[10:11], v[202:203]
	v_pk_mul_f32 v[6:7], v[6:7], v[198:199]
	v_pk_mul_f32 v[16:17], v[16:17], v[208:209]
	v_pk_mul_f32 v[12:13], v[12:13], v[204:205]
	v_pk_mul_f32 v[8:9], v[8:9], v[200:201]
	v_pk_mul_f32 v[4:5], v[4:5], v[196:197]
	v_pk_mul_f32 v[2:3], v[2:3], v[194:195]
	v_pk_mul_f32 v[30:31], v[30:31], v[206:207]
	v_pk_mul_f32 v[26:27], v[26:27], v[202:203]
	v_pk_mul_f32 v[22:23], v[22:23], v[198:199]
	v_pk_mul_f32 v[32:33], v[32:33], v[208:209]
	v_pk_mul_f32 v[28:29], v[28:29], v[204:205]
	v_pk_mul_f32 v[24:25], v[24:25], v[200:201]
	v_pk_mul_f32 v[20:21], v[20:21], v[196:197]
	v_pk_mul_f32 v[18:19], v[18:19], v[194:195]
	v_pk_mul_f32 v[46:47], v[46:47], v[206:207]
	v_pk_mul_f32 v[42:43], v[42:43], v[202:203]
	v_pk_mul_f32 v[38:39], v[38:39], v[198:199]
	v_pk_mul_f32 v[48:49], v[48:49], v[208:209]
	v_pk_mul_f32 v[44:45], v[44:45], v[204:205]
	v_pk_mul_f32 v[40:41], v[40:41], v[200:201]
	v_pk_mul_f32 v[36:37], v[36:37], v[196:197]
	v_pk_mul_f32 v[34:35], v[34:35], v[194:195]
	v_pk_mul_f32 v[62:63], v[62:63], v[206:207]
	v_pk_mul_f32 v[58:59], v[58:59], v[202:203]
	v_pk_mul_f32 v[54:55], v[54:55], v[198:199]
	v_pk_mul_f32 v[64:65], v[64:65], v[208:209]
	v_pk_mul_f32 v[60:61], v[60:61], v[204:205]
	v_pk_mul_f32 v[56:57], v[56:57], v[200:201]
	v_pk_mul_f32 v[52:53], v[52:53], v[196:197]
	v_pk_mul_f32 v[50:51], v[50:51], v[194:195]
	v_pk_mul_f32 v[78:79], v[78:79], v[206:207]
	v_pk_mul_f32 v[74:75], v[74:75], v[202:203]
	v_pk_mul_f32 v[70:71], v[70:71], v[198:199]
	v_pk_mul_f32 v[80:81], v[80:81], v[208:209]
	v_pk_mul_f32 v[76:77], v[76:77], v[204:205]
	v_pk_mul_f32 v[72:73], v[72:73], v[200:201]
	v_pk_mul_f32 v[68:69], v[68:69], v[196:197]
	v_pk_mul_f32 v[66:67], v[66:67], v[194:195]
	v_pk_mul_f32 v[94:95], v[94:95], v[206:207]
	v_pk_mul_f32 v[90:91], v[90:91], v[202:203]
	v_pk_mul_f32 v[86:87], v[86:87], v[198:199]
	v_pk_mul_f32 v[96:97], v[96:97], v[208:209]
	v_pk_mul_f32 v[92:93], v[92:93], v[204:205]
	v_pk_mul_f32 v[88:89], v[88:89], v[200:201]
	v_pk_mul_f32 v[84:85], v[84:85], v[196:197]
	v_pk_mul_f32 v[82:83], v[82:83], v[194:195]
	v_pk_mul_f32 v[110:111], v[110:111], v[206:207]
	v_pk_mul_f32 v[106:107], v[106:107], v[202:203]
	v_pk_mul_f32 v[102:103], v[102:103], v[198:199]
	v_pk_mul_f32 v[112:113], v[112:113], v[208:209]
	v_pk_mul_f32 v[108:109], v[108:109], v[204:205]
	v_pk_mul_f32 v[104:105], v[104:105], v[200:201]
	v_pk_mul_f32 v[100:101], v[100:101], v[196:197]
	v_pk_mul_f32 v[98:99], v[98:99], v[194:195]
	v_pk_mul_f32 v[126:127], v[126:127], v[206:207]
	v_pk_mul_f32 v[122:123], v[122:123], v[202:203]
	v_pk_mul_f32 v[118:119], v[118:119], v[198:199]
	v_pk_mul_f32 v[128:129], v[128:129], v[208:209]
	v_pk_mul_f32 v[124:125], v[124:125], v[204:205]
	v_pk_mul_f32 v[120:121], v[120:121], v[200:201]
	v_pk_mul_f32 v[116:117], v[116:117], v[196:197]
	v_pk_mul_f32 v[114:115], v[114:115], v[194:195]
	s_branch .LBB0_682
